# band: dequeue atomic prefetched at epilogue start, gate loads issued before the loop-exit barrier, bias lookups batched per score block (on v3)
# baseline (speedup 1.0000x reference)
; #define LAS __attribute__((address_space(3)))
; __device__ __forceinline__ unsigned row_addr(int lane, int s) { return off_b((unsigned)(lane & 15), (unsigned)(4 * s + (lane >> 4))); }
; __device__ __forceinline__ void b_item(const Params& P, int layer, LAS unsigned char* lds, int item, int tid) {
;     ...
;     tile_load<256, 16>(Qt, pjp(proj, BQ, 128, h, tok0), 128, tid);
;     for (int i = tid; i < 257; i += 512) bias[i] = P.rel_bias[(size_t)(layer * 5 + h) * 257 + i];
;     const int jst = (8 - 4 * m) > 0 ? (8 - 4 * m) : 0;
;     const long krow = (long)b * SEQ + (long)(4 * m - 8) * 64;
;     const bf16_t* kbase = pjp(proj, BKC, 128, h, 0) + krow * 128; const bf16_t* vbase = pjp(proj, BV, 128, h, 0) + krow * 128;
;     unsigned soff[2];
; #pragma unroll
;     for (int u = 0; u < 2; ++u) { const unsigned i = tid + 512 * u, row = i >> 4, ch = (i & 15) ^ (((row & 3u) << 2) | ((row >> 2) & 3u)); soff[u] = row * 128 + ch * 8; }
;     const unsigned ldsw = (unsigned)__builtin_amdgcn_readfirstlane(w) * 1024u;
;     ...
;     B_DMA(jst, 0);
;     __syncthreads();
;     LAS unsigned char* Qw = Qt + 4096 * (qc * 4 + th * 2);
;     float mrun[2] = {-1e30f, -1e30f}, lrun[2] = {0.f, 0.f}; const float bfar = bias[256];
;     unsigned kaddr[4], vaddr[8];
; #pragma unroll
;     for (int kk = 0; kk < 4; ++kk) kaddr[kk] = row_addr(lane, kk);
; #pragma unroll
;     for (int vb = 0; vb < 8; ++vb) vaddr[vb] = tr_addr<true>(lane, vb);
.LBB0_139:
	s_or_b64 exec, exec, s[12:13]
	s_waitcnt vmcnt(0)
	v_ashrrev_i32_e32 v0, 31, v150
	v_lshrrev_b32_e32 v0, 28, v0
	v_add_u32_e32 v1, v150, v0
	v_ashrrev_i32_e32 v0, 4, v1
	v_and_b32_e32 v1, -16, v1
	v_sub_u32_e32 v2, v150, v1
	v_ashrrev_i32_e32 v1, 31, v0
	v_lshlrev_b64 v[96:97], 8, v[0:1]
	v_lshlrev_b32_e32 v1, 2, v0
	v_lshlrev_b32_e32 v9, 8, v0
	v_and_b32_e32 v1, 12, v1
	v_bfe_u32 v0, v0, 2, 2
	v_bitop3_b32 v0, v1, v2, v0 bitop3:0x36
	v_add_u32_e32 v151, 0x200, v150
	v_lshl_add_u32 v10, v0, 4, 0
	v_ashrrev_i32_e32 v0, 31, v151
	v_lshrrev_b32_e32 v0, 28, v0
	v_add_u32_e32 v1, v151, v0
	v_ashrrev_i32_e32 v0, 4, v1
	v_and_b32_e32 v1, -16, v1
	v_lshlrev_b32_e32 v98, 3, v2
	v_sub_u32_e32 v2, v151, v1
	v_ashrrev_i32_e32 v1, 31, v0
	v_lshlrev_b64 v[100:101], 8, v[0:1]
	v_lshlrev_b32_e32 v1, 2, v0
	v_lshlrev_b32_e32 v11, 8, v0
	v_and_b32_e32 v1, 12, v1
	v_bfe_u32 v0, v0, 2, 2
	v_bitop3_b32 v0, v1, v2, v0 bitop3:0x36
	v_add_u32_e32 v1, 0x400, v150
	v_lshl_add_u32 v12, v0, 4, 0
	v_ashrrev_i32_e32 v0, 31, v1
	v_lshrrev_b32_e32 v0, 28, v0
	v_lshlrev_b32_e32 v102, 3, v2
	v_add_u32_e32 v2, v1, v0
	v_ashrrev_i32_e32 v0, 4, v2
	v_and_b32_e32 v2, -16, v2
	v_sub_u32_e32 v2, v1, v2
	v_ashrrev_i32_e32 v1, 31, v0
	v_lshlrev_b64 v[104:105], 8, v[0:1]
	v_lshlrev_b32_e32 v1, 2, v0
	v_lshlrev_b32_e32 v13, 8, v0
	v_and_b32_e32 v1, 12, v1
	v_bfe_u32 v0, v0, 2, 2
	v_bitop3_b32 v0, v1, v2, v0 bitop3:0x36
	v_add_u32_e32 v1, 0x600, v150
	v_lshl_add_u32 v14, v0, 4, 0
	v_ashrrev_i32_e32 v0, 31, v1
	v_lshrrev_b32_e32 v0, 28, v0
	v_lshlrev_b32_e32 v106, 3, v2
	v_add_u32_e32 v2, v1, v0
	v_ashrrev_i32_e32 v0, 4, v2
	v_and_b32_e32 v2, -16, v2
	v_sub_u32_e32 v2, v1, v2
	v_ashrrev_i32_e32 v1, 31, v0
	v_lshlrev_b64 v[108:109], 8, v[0:1]
	v_lshlrev_b32_e32 v1, 2, v0
	v_lshlrev_b32_e32 v15, 8, v0
	v_and_b32_e32 v1, 12, v1
	v_bfe_u32 v0, v0, 2, 2
	v_bitop3_b32 v0, v1, v2, v0 bitop3:0x36
	v_add_u32_e32 v1, 0x800, v150
	v_lshl_add_u32 v16, v0, 4, 0
	v_ashrrev_i32_e32 v0, 31, v1
	v_lshrrev_b32_e32 v0, 28, v0
	v_lshlrev_b32_e32 v110, 3, v2
	v_add_u32_e32 v2, v1, v0
	v_ashrrev_i32_e32 v0, 4, v2
	v_and_b32_e32 v2, -16, v2
	v_sub_u32_e32 v2, v1, v2
	v_ashrrev_i32_e32 v1, 31, v0
	v_lshlrev_b64 v[112:113], 8, v[0:1]
	v_lshlrev_b32_e32 v1, 2, v0
	v_lshlrev_b32_e32 v17, 8, v0
	v_and_b32_e32 v1, 12, v1
	v_bfe_u32 v0, v0, 2, 2
	v_bitop3_b32 v0, v1, v2, v0 bitop3:0x36
	v_add_u32_e32 v1, 0xa00, v150
	v_lshl_add_u32 v18, v0, 4, 0
	v_ashrrev_i32_e32 v0, 31, v1
	v_lshrrev_b32_e32 v0, 28, v0
	v_lshlrev_b32_e32 v114, 3, v2
	v_add_u32_e32 v2, v1, v0
	v_ashrrev_i32_e32 v0, 4, v2
	v_and_b32_e32 v2, -16, v2
	v_sub_u32_e32 v2, v1, v2
	v_ashrrev_i32_e32 v1, 31, v0
	v_lshlrev_b64 v[116:117], 8, v[0:1]
	v_lshlrev_b32_e32 v1, 2, v0
	v_lshlrev_b32_e32 v19, 8, v0
	v_and_b32_e32 v1, 12, v1
	v_bfe_u32 v0, v0, 2, 2
	v_bitop3_b32 v0, v1, v2, v0 bitop3:0x36
	v_add_u32_e32 v1, 0xc00, v150
	v_lshl_add_u32 v20, v0, 4, 0
	v_ashrrev_i32_e32 v0, 31, v1
	v_lshrrev_b32_e32 v0, 28, v0
	v_lshlrev_b32_e32 v118, 3, v2
	v_add_u32_e32 v2, v1, v0
	v_ashrrev_i32_e32 v0, 4, v2
	v_and_b32_e32 v2, -16, v2
	v_sub_u32_e32 v2, v1, v2
	v_ashrrev_i32_e32 v1, 31, v0
	v_lshlrev_b64 v[120:121], 8, v[0:1]
	v_lshlrev_b32_e32 v1, 2, v0
	v_lshlrev_b32_e32 v21, 8, v0
	v_and_b32_e32 v1, 12, v1
	v_bfe_u32 v0, v0, 2, 2
	v_lshlrev_b32_e32 v7, 2, v150
	v_bfe_u32 v8, v150, 4, 2
	v_and_b32_e32 v192, 15, v150
	v_bitop3_b32 v0, v1, v2, v0 bitop3:0x36
	v_add_u32_e32 v1, 0xe00, v150
	v_and_b32_e32 v7, 12, v7
	v_bfe_u32 v25, v150, 2, 2
	v_lshl_add_u32 v22, v0, 4, 0
	v_ashrrev_i32_e32 v0, 31, v1
	v_lshlrev_b32_e32 v6, 8, v192
	v_bitop3_b32 v26, v7, v8, v25 bitop3:0x36
	v_lshrrev_b32_e32 v0, 28, v0
	v_lshl_or_b32 v193, v26, 4, v6
	v_or_b32_e32 v26, 4, v8
	v_lshlrev_b32_e32 v122, 3, v2
	v_add_u32_e32 v2, v1, v0
	v_bitop3_b32 v26, v7, v26, v25 bitop3:0x36
	v_ashrrev_i32_e32 v0, 4, v2
	v_and_b32_e32 v2, -16, v2
	v_lshl_or_b32 v194, v26, 4, v6
	v_or_b32_e32 v26, 8, v8
	v_readlane_b32 s40, v247, 14
	v_sub_u32_e32 v2, v1, v2
	v_ashrrev_i32_e32 v1, 31, v0
	v_bitop3_b32 v26, v7, v26, v25 bitop3:0x36
	v_readlane_b32 s50, v247, 24
	v_readlane_b32 s0, v247, 48
	v_lshlrev_b64 v[124:125], 8, v[0:1]
	v_lshlrev_b32_e32 v1, 2, v0
	v_lshl_or_b32 v195, v26, 4, v6
	v_or_b32_e32 v26, 12, v8
	v_readlane_b32 s51, v247, 25
	v_readlane_b32 s1, v247, 49
	s_add_u32 s8, s50, s0
	v_lshlrev_b32_e32 v23, 8, v0
	v_and_b32_e32 v1, 12, v1
	v_bfe_u32 v0, v0, 2, 2
	v_lshlrev_b32_e32 v4, 3, v150
	v_bitop3_b32 v7, v7, v26, v25 bitop3:0x36
	s_addc_u32 s9, s51, s1
	s_ashr_i32 s85, s84, 31
	v_lshlrev_b32_e32 v126, 3, v2
	v_bitop3_b32 v0, v1, v2, v0 bitop3:0x36
	v_and_b32_e32 v2, 0xffffff80, v4
	v_lshl_or_b32 v196, v7, 4, v6
	v_bfe_u32 v6, v150, 1, 1
	v_lshlrev_b32_e32 v7, 6, v150
	v_and_b32_e32 v25, 12, v150
	v_and_b32_e32 v4, 8, v4
	s_lshl_b64 s[0:1], s[84:85], 2
	v_or_b32_e32 v26, v8, v25
	v_and_or_b32 v197, v7, s92, v4
	v_bitop3_b32 v4, v8, v6, v25 bitop3:0x36
	s_add_u32 s0, s4, s0
	v_lshlrev_b32_e32 v198, 4, v4
	v_bitop3_b32 v4, v6, v26, 2 bitop3:0x36
	v_readlane_b32 s48, v247, 22
	s_addc_u32 s1, s5, s1
	v_lshlrev_b32_e32 v199, 4, v4
	v_bitop3_b32 v4, v6, v26, 4 bitop3:0x36
	v_readlane_b32 s49, v247, 23
	s_add_u32 s48, s0, 0x33983800
	v_lshlrev_b32_e32 v200, 4, v4
	v_bitop3_b32 v4, v6, v26, 6 bitop3:0x36
	s_addc_u32 s49, s1, 0
	v_lshlrev_b32_e32 v201, 4, v4
	v_bitop3_b32 v4, v6, v26, 8 bitop3:0x36
	v_ashrrev_i32_e32 v190, 6, v150
	s_add_u32 s60, s4, 0x18c00000
	v_lshlrev_b32_e32 v202, 4, v4
	v_bitop3_b32 v4, v6, v26, 10 bitop3:0x36
	v_ashrrev_i32_e32 v191, 7, v150
	v_and_b32_e32 v5, 1, v190
	s_addc_u32 s61, s5, 0
	v_lshlrev_b32_e32 v203, 4, v4
	v_bitop3_b32 v4, v6, v26, 12 bitop3:0x36
; __device__ __forceinline__ float rcp_f(float v) { return __builtin_amdgcn_rcpf(v); }
; __device__ __forceinline__ unsigned row_addr(int lane, int s) { return off_b((unsigned)(lane & 15), (unsigned)(4 * s + (lane >> 4))); }
; __device__ __forceinline__ void b_item(const Params& P, int layer, LAS unsigned char* lds, int item, int tid) {
;     ...
;     float mrun[2] = {-1e30f, -1e30f}, lrun[2] = {0.f, 0.f}; const float bfar = bias[256];
;     unsigned kaddr[4], vaddr[8];
; #pragma unroll
;     for (int kk = 0; kk < 4; ++kk) kaddr[kk] = row_addr(lane, kk);
; #pragma unroll
;     for (int vb = 0; vb < 8; ++vb) vaddr[vb] = tr_addr<true>(lane, vb);
;     ...
;     __syncthreads();
;     ...
; #pragma unroll
;     for (int u = 0; u < 2; ++u) {
;         float l = lrun[u]; l += __shfl_xor(l, 16); l += __shfl_xor(l, 32);
;         const float inv = rcp_f(l);
;         const size_t tok = tok0 + 64 * qc + 32 * th + 16 * u + c15;
;         const bf16_t* gate = pjp(proj, BG, 128, h, tok);
;         bf16_t* y = (bf16_t*)(P.ws + (layer == 0 ? WS_H : WS_D1)) + tok * DM + YB + h * 128;
; #pragma unroll
;         for (int vb = 0; vb < 8; ++vb) { const int v0 = 16 * vb + 4 * g; const u32x2 gt2 = *(const u32x2*)(gate + v0);
	s_add_u32 s39, s4, 0x1dc00000
	v_lshlrev_b32_e32 v204, 4, v4
	v_bitop3_b32 v4, v6, v26, 14 bitop3:0x36
	v_lshlrev_b32_e32 v25, 5, v5
	v_lshlrev_b32_e32 v6, 14, v191
	v_lshlrev_b32_e32 v5, 13, v5
	v_lshl_add_u32 v24, v0, 4, 0
	s_addc_u32 s62, s5, 0
	v_lshrrev_b32_e32 v0, 2, v150
	v_add3_u32 v206, 0, v6, v5
	v_max_i32_e32 v5, 0xffffff01, v150
	v_readlane_b32 s42, v247, 16
	v_readlane_b32 s43, v247, 17
	s_movk_i32 s0, 0x101
	v_bfe_u32 v1, v150, 6, 2
	v_and_b32_e32 v0, 12, v0
	s_add_u32 s63, s4, 0x1b400000
	v_sub_u32_e32 v5, v5, v150
	v_cmp_gt_i32_e64 s[42:43], s0, v150
	v_bitop3_b32 v0, v0, v192, v1 bitop3:0x36
	s_addc_u32 s64, s5, 0
	s_add_i32 s0, s94, 4
	v_add_u32_e32 v5, 0x1ff, v5
	v_lshl_or_b32 v0, v0, 3, v2
	v_lshrrev_b32_e32 v2, 2, v151
	s_cmp_lt_u32 s0, 11
	v_lshrrev_b32_e32 v6, 9, v5
	v_and_b32_e32 v2, 12, v2
	s_cselect_b32 s0, s93, 0x33984000
	v_add_u32_e32 v6, 1, v6
	v_readlane_b32 s44, v247, 18
	v_readlane_b32 s45, v247, 19
	v_readlane_b32 s46, v247, 20
	v_readlane_b32 s47, v247, 21
	v_bitop3_b32 v1, v2, v192, v1 bitop3:0x36
	v_lshlrev_b32_e32 v2, 3, v151
	s_add_u32 s18, s4, s0
	s_movk_i32 s0, 0x1ff
	v_and_b32_e32 v208, 0xfffffe, v6
	v_lshlrev_b32_e32 v136, 3, v8
	v_and_b32_e32 v2, 0xffffff80, v2
	v_lshlrev_b32_e32 v152, 6, v191
	v_cmp_lt_u32_e64 s[44:45], s0, v5
	v_cmp_ne_u32_e64 s[46:47], v6, v208
	v_lshl_add_u64 v[6:7], s[4:5], 0, v[136:137]
	s_mov_b64 s[0:1], 0x20400000
	v_readlane_b32 s41, v247, 15
	v_lshl_or_b32 v2, v1, 3, v2
	v_mov_b32_e32 v1, v137
	v_mov_b32_e32 v3, v137
	v_lshlrev_b32_e32 v205, 4, v4
	v_lshlrev_b32_e32 v4, 2, v8
	v_lshl_add_u64 v[156:157], v[6:7], 0, s[0:1]
	v_readlane_b32 s0, v247, 7
	v_or_b32_e32 v5, v152, v25
	v_cmp_eq_u32_e64 s[40:41], 0, v150
	v_ashrrev_i32_e32 v99, 31, v98
	v_ashrrev_i32_e32 v103, 31, v102
	v_ashrrev_i32_e32 v107, 31, v106
	v_ashrrev_i32_e32 v111, 31, v110
	v_ashrrev_i32_e32 v115, 31, v114
	v_ashrrev_i32_e32 v119, 31, v118
	v_ashrrev_i32_e32 v123, 31, v122
	v_ashrrev_i32_e32 v127, 31, v126
	v_add_u32_e32 v207, 8, v191
	v_ashrrev_i32_e32 v153, 31, v152
	s_addc_u32 s19, s5, 0
	v_or_b32_e32 v154, v25, v192
	v_lshl_add_u32 v209, v208, 9, v150
	v_add_u32_e32 v210, s0, v189
	v_sub_u32_e32 v211, v5, v4
	v_mad_i32_i24 v212, v8, -4, v5
	v_add_u32_e32 v213, v10, v9
	v_add_u32_e32 v214, v12, v11
	v_add_u32_e32 v215, v14, v13
	v_add_u32_e32 v216, v16, v15
	v_add_u32_e32 v217, v18, v17
	v_add_u32_e32 v218, v20, v19
	v_add_u32_e32 v219, v22, v21
	v_add_u32_e32 v220, v24, v23
	v_lshlrev_b32_e32 v136, 1, v4
	v_lshlrev_b64 v[158:159], 1, v[0:1]
	v_lshlrev_b64 v[160:161], 1, v[2:3]
	v_readlane_b32 s52, v247, 26
	v_readlane_b32 s53, v247, 27
	v_readlane_b32 s54, v247, 28
	v_readlane_b32 s55, v247, 29
	s_and_saveexec_b64 s[0:1], s[40:41]
	s_cbranch_execz .Lbq_pre_skip
	v_mov_b32_e32 v246, 1
	global_atomic_add v246, v137, v246, s[48:49] sc0
	s_waitcnt vmcnt(0)
.Lbq_pre_skip:
	s_or_b64 exec, exec, s[0:1]
	s_branch .LBB0_142
.LBB0_140:
	v_lshl_add_u64 v[64:65], s[50:51], 0, v[152:153]
	v_or_b32_e32 v64, v64, v154
	v_lshl_add_u64 v[66:67], v[64:65], 0, s[12:13]
	v_lshlrev_b64 v[66:67], 8, v[66:67]
	v_lshl_add_u64 v[70:71], v[156:157], 0, v[66:67]
	s_and_saveexec_b64 s[14:15], s[40:41]
	s_cbranch_execz .Lbq_ep_skip
	v_mov_b32_e32 v246, 1
	global_atomic_add v246, v137, v246, s[48:49] sc0
.Lbq_ep_skip:
	s_or_b64 exec, exec, s[14:15]
	v_or_b32_e32 v162, 16, v64
	v_mov_b32_e32 v163, v65
	v_lshl_add_u64 v[162:163], v[162:163], 0, s[12:13]
	v_lshlrev_b64 v[162:163], 8, v[162:163]
	v_lshl_add_u64 v[162:163], v[156:157], 0, v[162:163]
	global_load_dwordx2 v[84:85], v[70:71], off
	global_load_dwordx2 v[86:87], v[70:71], off offset:32
	global_load_dwordx2 v[88:89], v[70:71], off offset:64
	global_load_dwordx2 v[90:91], v[70:71], off offset:96
	global_load_dwordx2 v[92:93], v[70:71], off offset:128
	global_load_dwordx2 v[94:95], v[70:71], off offset:160
	global_load_dwordx2 v[164:165], v[70:71], off offset:192
	global_load_dwordx2 v[166:167], v[70:71], off offset:224
	global_load_dwordx2 v[168:169], v[162:163], off
	global_load_dwordx2 v[170:171], v[162:163], off offset:32
	global_load_dwordx2 v[172:173], v[162:163], off offset:64
	global_load_dwordx2 v[174:175], v[162:163], off offset:96
	global_load_dwordx2 v[228:229], v[162:163], off offset:128
	global_load_dwordx2 v[230:231], v[162:163], off offset:160
	global_load_dwordx2 v[226:227], v[162:163], off offset:192
	global_load_dwordx2 v[162:163], v[162:163], off offset:224
	s_waitcnt lgkmcnt(0)
	s_barrier
; __device__ __forceinline__ unsigned cvt_pk_bf16(float lo, float hi) { const f32x2 f = {lo, hi}; const bf16x2_t v = __builtin_convertvector(f, bf16x2_t); return __builtin_bit_cast(unsigned, v); }
; __device__ __forceinline__ float bflo(unsigned u) { return __uint_as_float(u << 16); }
; __device__ __forceinline__ float bfhi(unsigned u) { return __uint_as_float(u & 0xffff0000u); }
; __device__ __forceinline__ float rcp_f(float v) { return __builtin_amdgcn_rcpf(v); }
; __device__ __forceinline__ float silu_f(float v) { return v * rcp_f(1.f + __expf(-v)); }
; __device__ __forceinline__ void b_item(const Params& P, int layer, LAS unsigned char* lds, int item, int tid) {
;     ...
;     for (int u = 0; u < 2; ++u) {
;         float l = lrun[u]; l += __shfl_xor(l, 16); l += __shfl_xor(l, 32);
;         const float inv = rcp_f(l);
;         const size_t tok = tok0 + 64 * qc + 32 * th + 16 * u + c15;
;         const bf16_t* gate = pjp(proj, BG, 128, h, tok);
;         bf16_t* y = (bf16_t*)(P.ws + (layer == 0 ? WS_H : WS_D1)) + tok * DM + YB + h * 128;
; #pragma unroll
;         for (int vb = 0; vb < 8; ++vb) { const int v0 = 16 * vb + 4 * g; const u32x2 gt2 = *(const u32x2*)(gate + v0);
;             u32x2 o; o.x = cvt_pk_bf16(acco[u][vb][0] * inv * silu_f(bflo(gt2.x)), acco[u][vb][1] * inv * silu_f(bfhi(gt2.x)));
;             o.y = cvt_pk_bf16(acco[u][vb][2] * inv * silu_f(bflo(gt2.y)), acco[u][vb][3] * inv * silu_f(bfhi(gt2.y)));
;             *(u32x2*)(y + v0) = o; }
	v_and_b32_e32 v67, 64, v184
	v_xor_b32_e32 v66, 16, v184
	v_add_u32_e32 v67, 64, v67
	v_cmp_lt_i32_e32 vcc, v66, v67
	v_xor_b32_e32 v68, 32, v184
	s_lshl_b32 s0, s10, 7
	v_cndmask_b32_e32 v66, v184, v66, vcc
	v_lshlrev_b32_e32 v69, 2, v66
	ds_bpermute_b32 v73, v69, v225
	v_cmp_lt_i32_e32 vcc, v68, v67
	s_ashr_i32 s1, s0, 31
	v_lshlrev_b64 v[66:67], 12, v[64:65]
	v_cndmask_b32_e32 v68, v184, v68, vcc
	v_lshlrev_b32_e32 v72, 2, v68
	s_waitcnt lgkmcnt(0)
	v_add_f32_e32 v68, v225, v73
	ds_bpermute_b32 v73, v72, v68
	s_lshl_b64 s[0:1], s[0:1], 1
	v_lshl_add_u64 v[66:67], s[18:19], 0, v[66:67]
	v_lshl_add_u64 v[66:67], v[66:67], 0, s[0:1]
	v_lshl_add_u64 v[66:67], v[66:67], 0, v[136:137]
	s_waitcnt lgkmcnt(0)
	v_add_f32_e32 v68, v68, v73
	v_rcp_f32_e32 v68, v68
	v_or_b32_e32 v64, 16, v64
	v_pk_mul_f32 v[60:61], v[60:61], v[68:69] op_sel_hi:[1,0]
	v_pk_mul_f32 v[62:63], v[62:63], v[68:69] op_sel_hi:[1,0]
	v_pk_mul_f32 v[56:57], v[56:57], v[68:69] op_sel_hi:[1,0]
	v_pk_mul_f32 v[58:59], v[58:59], v[68:69] op_sel_hi:[1,0]
	v_pk_mul_f32 v[52:53], v[52:53], v[68:69] op_sel_hi:[1,0]
	v_pk_mul_f32 v[54:55], v[54:55], v[68:69] op_sel_hi:[1,0]
	v_pk_mul_f32 v[48:49], v[48:49], v[68:69] op_sel_hi:[1,0]
	v_pk_mul_f32 v[50:51], v[50:51], v[68:69] op_sel_hi:[1,0]
	v_pk_mul_f32 v[44:45], v[44:45], v[68:69] op_sel_hi:[1,0]
	v_pk_mul_f32 v[46:47], v[46:47], v[68:69] op_sel_hi:[1,0]
	v_pk_mul_f32 v[40:41], v[40:41], v[68:69] op_sel_hi:[1,0]
	v_pk_mul_f32 v[42:43], v[42:43], v[68:69] op_sel_hi:[1,0]
	v_pk_mul_f32 v[36:37], v[36:37], v[68:69] op_sel_hi:[1,0]
	v_pk_mul_f32 v[38:39], v[38:39], v[68:69] op_sel_hi:[1,0]
	v_pk_mul_f32 v[32:33], v[32:33], v[68:69] op_sel_hi:[1,0]
	v_pk_mul_f32 v[34:35], v[34:35], v[68:69] op_sel_hi:[1,0]
	s_waitcnt vmcnt(15)
	v_lshlrev_b32_e32 v76, 16, v84
	v_and_b32_e32 v77, 0xffff0000, v84
	v_lshlrev_b32_e32 v74, 16, v85
	v_and_b32_e32 v75, 0xffff0000, v85
	v_mul_f32_e32 v73, 0xbfb8aa3b, v76
	v_mul_f32_e32 v78, 0xbfb8aa3b, v77
	v_mul_f32_e32 v79, 0xbfb8aa3b, v74
	v_mul_f32_e32 v80, 0xbfb8aa3b, v75
	v_exp_f32_e32 v73, v73
	v_exp_f32_e32 v78, v78
	v_exp_f32_e32 v79, v79
	v_exp_f32_e32 v80, v80
	v_add_f32_e32 v73, 1.0, v73
	v_add_f32_e32 v81, 1.0, v78
	v_add_f32_e32 v82, 1.0, v79
	v_add_f32_e32 v83, 1.0, v80
	v_rcp_f32_e32 v78, v73
	v_rcp_f32_e32 v79, v81
	v_rcp_f32_e32 v80, v82
	v_rcp_f32_e32 v81, v83
	v_pk_mul_f32 v[76:77], v[78:79], v[76:77]
	s_nop 0
	v_pk_mul_f32 v[60:61], v[60:61], v[76:77]
	v_pk_mul_f32 v[74:75], v[80:81], v[74:75]
	v_cvt_pk_bf16_f32 v60, v60, v61
	v_pk_mul_f32 v[62:63], v[62:63], v[74:75]
	s_nop 0
	v_cvt_pk_bf16_f32 v61, v62, v63
	global_store_dwordx2 v[66:67], v[60:61], off offset:1536
	s_waitcnt vmcnt(15)
	v_lshlrev_b32_e32 v62, 16, v86
	v_and_b32_e32 v63, 0xffff0000, v86
	v_lshlrev_b32_e32 v60, 16, v87
	v_and_b32_e32 v61, 0xffff0000, v87
	v_mul_f32_e32 v73, 0xbfb8aa3b, v62
	v_mul_f32_e32 v74, 0xbfb8aa3b, v63
	v_mul_f32_e32 v75, 0xbfb8aa3b, v60
	v_mul_f32_e32 v76, 0xbfb8aa3b, v61
	v_exp_f32_e32 v73, v73
	v_exp_f32_e32 v74, v74
	v_exp_f32_e32 v75, v75
	v_exp_f32_e32 v76, v76
	v_add_f32_e32 v73, 1.0, v73
	v_add_f32_e32 v77, 1.0, v74
	v_add_f32_e32 v78, 1.0, v75
	v_add_f32_e32 v79, 1.0, v76
	v_rcp_f32_e32 v74, v73
	v_rcp_f32_e32 v75, v77
	v_rcp_f32_e32 v76, v78
	v_rcp_f32_e32 v77, v79
	v_pk_mul_f32 v[62:63], v[74:75], v[62:63]
	s_nop 0
	v_pk_mul_f32 v[56:57], v[56:57], v[62:63]
	v_pk_mul_f32 v[60:61], v[76:77], v[60:61]
	v_cvt_pk_bf16_f32 v56, v56, v57
	v_pk_mul_f32 v[58:59], v[58:59], v[60:61]
	s_nop 0
	v_cvt_pk_bf16_f32 v57, v58, v59
	global_store_dwordx2 v[66:67], v[56:57], off offset:1568
	s_waitcnt vmcnt(15)
	v_lshlrev_b32_e32 v58, 16, v88
	v_and_b32_e32 v59, 0xffff0000, v88
	v_lshlrev_b32_e32 v56, 16, v89
	v_and_b32_e32 v57, 0xffff0000, v89
	v_mul_f32_e32 v60, 0xbfb8aa3b, v58
	v_mul_f32_e32 v61, 0xbfb8aa3b, v59
	v_mul_f32_e32 v62, 0xbfb8aa3b, v56
	v_mul_f32_e32 v63, 0xbfb8aa3b, v57
	v_exp_f32_e32 v60, v60
	v_exp_f32_e32 v61, v61
	v_exp_f32_e32 v62, v62
	v_exp_f32_e32 v63, v63
	v_add_f32_e32 v60, 1.0, v60
	v_add_f32_e32 v61, 1.0, v61
	v_add_f32_e32 v62, 1.0, v62
	v_add_f32_e32 v63, 1.0, v63
	v_rcp_f32_e32 v60, v60
	v_rcp_f32_e32 v61, v61
	v_rcp_f32_e32 v62, v62
	v_rcp_f32_e32 v63, v63
	v_pk_mul_f32 v[58:59], v[60:61], v[58:59]
	s_nop 0
	v_pk_mul_f32 v[52:53], v[52:53], v[58:59]
	v_pk_mul_f32 v[56:57], v[62:63], v[56:57]
	v_cvt_pk_bf16_f32 v52, v52, v53
	v_pk_mul_f32 v[54:55], v[54:55], v[56:57]
	s_nop 0
	v_cvt_pk_bf16_f32 v53, v54, v55
	global_store_dwordx2 v[66:67], v[52:53], off offset:1600
	s_waitcnt vmcnt(15)
	v_lshlrev_b32_e32 v54, 16, v90
	v_and_b32_e32 v55, 0xffff0000, v90
	v_lshlrev_b32_e32 v52, 16, v91
	v_and_b32_e32 v53, 0xffff0000, v91
	v_mul_f32_e32 v56, 0xbfb8aa3b, v54
	v_mul_f32_e32 v57, 0xbfb8aa3b, v55
	v_mul_f32_e32 v58, 0xbfb8aa3b, v52
	v_mul_f32_e32 v59, 0xbfb8aa3b, v53
	v_exp_f32_e32 v56, v56
	v_exp_f32_e32 v57, v57
	v_exp_f32_e32 v58, v58
	v_exp_f32_e32 v59, v59
	v_add_f32_e32 v56, 1.0, v56
	v_add_f32_e32 v57, 1.0, v57
	v_add_f32_e32 v58, 1.0, v58
	v_add_f32_e32 v59, 1.0, v59
	v_rcp_f32_e32 v56, v56
	v_rcp_f32_e32 v57, v57
	v_rcp_f32_e32 v58, v58
	v_rcp_f32_e32 v59, v59
	v_pk_mul_f32 v[54:55], v[56:57], v[54:55]
	s_nop 0
	v_pk_mul_f32 v[48:49], v[48:49], v[54:55]
	v_pk_mul_f32 v[52:53], v[58:59], v[52:53]
	v_cvt_pk_bf16_f32 v48, v48, v49
	v_pk_mul_f32 v[50:51], v[50:51], v[52:53]
	s_nop 0
	v_cvt_pk_bf16_f32 v49, v50, v51
	global_store_dwordx2 v[66:67], v[48:49], off offset:1632
	s_waitcnt vmcnt(15)
; __device__ __forceinline__ unsigned cvt_pk_bf16(float lo, float hi) { const f32x2 f = {lo, hi}; const bf16x2_t v = __builtin_convertvector(f, bf16x2_t); return __builtin_bit_cast(unsigned, v); }
; __device__ __forceinline__ float bflo(unsigned u) { return __uint_as_float(u << 16); }
; __device__ __forceinline__ float bfhi(unsigned u) { return __uint_as_float(u & 0xffff0000u); }
; __device__ __forceinline__ float rcp_f(float v) { return __builtin_amdgcn_rcpf(v); }
; __device__ __forceinline__ float silu_f(float v) { return v * rcp_f(1.f + __expf(-v)); }
; __device__ __forceinline__ void b_item(const Params& P, int layer, LAS unsigned char* lds, int item, int tid) {
;     ...
;     for (int u = 0; u < 2; ++u) {
;         float l = lrun[u]; l += __shfl_xor(l, 16); l += __shfl_xor(l, 32);
;         const float inv = rcp_f(l);
;         const size_t tok = tok0 + 64 * qc + 32 * th + 16 * u + c15;
;         const bf16_t* gate = pjp(proj, BG, 128, h, tok);
;         bf16_t* y = (bf16_t*)(P.ws + (layer == 0 ? WS_H : WS_D1)) + tok * DM + YB + h * 128;
; #pragma unroll
;         for (int vb = 0; vb < 8; ++vb) { const int v0 = 16 * vb + 4 * g; const u32x2 gt2 = *(const u32x2*)(gate + v0);
;             u32x2 o; o.x = cvt_pk_bf16(acco[u][vb][0] * inv * silu_f(bflo(gt2.x)), acco[u][vb][1] * inv * silu_f(bfhi(gt2.x)));
;             o.y = cvt_pk_bf16(acco[u][vb][2] * inv * silu_f(bflo(gt2.y)), acco[u][vb][3] * inv * silu_f(bfhi(gt2.y)));
;             *(u32x2*)(y + v0) = o; }
	v_lshlrev_b32_e32 v50, 16, v92
	v_and_b32_e32 v51, 0xffff0000, v92
	v_lshlrev_b32_e32 v48, 16, v93
	v_and_b32_e32 v49, 0xffff0000, v93
	v_mul_f32_e32 v52, 0xbfb8aa3b, v50
	v_mul_f32_e32 v53, 0xbfb8aa3b, v51
	v_mul_f32_e32 v54, 0xbfb8aa3b, v48
	v_mul_f32_e32 v55, 0xbfb8aa3b, v49
	v_exp_f32_e32 v52, v52
	v_exp_f32_e32 v53, v53
	v_exp_f32_e32 v54, v54
	v_exp_f32_e32 v55, v55
	v_add_f32_e32 v52, 1.0, v52
	v_add_f32_e32 v53, 1.0, v53
	v_add_f32_e32 v54, 1.0, v54
	v_add_f32_e32 v55, 1.0, v55
	v_rcp_f32_e32 v52, v52
	v_rcp_f32_e32 v53, v53
	v_rcp_f32_e32 v54, v54
	v_rcp_f32_e32 v55, v55
	v_pk_mul_f32 v[50:51], v[52:53], v[50:51]
	s_nop 0
	v_pk_mul_f32 v[44:45], v[44:45], v[50:51]
	v_pk_mul_f32 v[48:49], v[54:55], v[48:49]
	v_cvt_pk_bf16_f32 v44, v44, v45
	v_pk_mul_f32 v[46:47], v[46:47], v[48:49]
	s_nop 0
	v_cvt_pk_bf16_f32 v45, v46, v47
	global_store_dwordx2 v[66:67], v[44:45], off offset:1664
	s_waitcnt vmcnt(15)
	v_lshlrev_b32_e32 v46, 16, v94
	v_and_b32_e32 v47, 0xffff0000, v94
	v_lshlrev_b32_e32 v44, 16, v95
	v_and_b32_e32 v45, 0xffff0000, v95
	v_mul_f32_e32 v48, 0xbfb8aa3b, v46
	v_mul_f32_e32 v49, 0xbfb8aa3b, v47
	v_mul_f32_e32 v50, 0xbfb8aa3b, v44
	v_mul_f32_e32 v51, 0xbfb8aa3b, v45
	v_exp_f32_e32 v48, v48
	v_exp_f32_e32 v49, v49
	v_exp_f32_e32 v50, v50
	v_exp_f32_e32 v51, v51
	v_add_f32_e32 v48, 1.0, v48
	v_add_f32_e32 v49, 1.0, v49
	v_add_f32_e32 v50, 1.0, v50
	v_add_f32_e32 v51, 1.0, v51
	v_rcp_f32_e32 v48, v48
	v_rcp_f32_e32 v49, v49
	v_rcp_f32_e32 v50, v50
	v_rcp_f32_e32 v51, v51
	v_pk_mul_f32 v[46:47], v[48:49], v[46:47]
	s_nop 0
	v_pk_mul_f32 v[40:41], v[40:41], v[46:47]
	v_pk_mul_f32 v[44:45], v[50:51], v[44:45]
	v_cvt_pk_bf16_f32 v40, v40, v41
	v_pk_mul_f32 v[42:43], v[42:43], v[44:45]
	s_nop 0
	v_cvt_pk_bf16_f32 v41, v42, v43
	global_store_dwordx2 v[66:67], v[40:41], off offset:1696
	s_waitcnt vmcnt(15)
	v_lshlrev_b32_e32 v42, 16, v164
	v_and_b32_e32 v43, 0xffff0000, v164
	v_lshlrev_b32_e32 v40, 16, v165
	v_and_b32_e32 v41, 0xffff0000, v165
	v_mul_f32_e32 v44, 0xbfb8aa3b, v42
	v_mul_f32_e32 v45, 0xbfb8aa3b, v43
	v_mul_f32_e32 v46, 0xbfb8aa3b, v40
	v_mul_f32_e32 v47, 0xbfb8aa3b, v41
	v_exp_f32_e32 v44, v44
	v_exp_f32_e32 v45, v45
	v_exp_f32_e32 v46, v46
	v_exp_f32_e32 v47, v47
	v_add_f32_e32 v44, 1.0, v44
	v_add_f32_e32 v45, 1.0, v45
	v_add_f32_e32 v46, 1.0, v46
	v_add_f32_e32 v47, 1.0, v47
	v_rcp_f32_e32 v44, v44
	v_rcp_f32_e32 v45, v45
	v_rcp_f32_e32 v46, v46
	v_rcp_f32_e32 v47, v47
	v_pk_mul_f32 v[42:43], v[44:45], v[42:43]
	s_nop 0
	v_pk_mul_f32 v[36:37], v[36:37], v[42:43]
	v_pk_mul_f32 v[40:41], v[46:47], v[40:41]
	v_cvt_pk_bf16_f32 v36, v36, v37
	v_pk_mul_f32 v[38:39], v[38:39], v[40:41]
	s_nop 0
	v_cvt_pk_bf16_f32 v37, v38, v39
	global_store_dwordx2 v[66:67], v[36:37], off offset:1728
	v_lshl_add_u64 v[36:37], v[64:65], 0, s[12:13]
	v_lshlrev_b64 v[36:37], 8, v[36:37]
	v_lshl_add_u64 v[36:37], v[156:157], 0, v[36:37]
	s_waitcnt vmcnt(15)
	v_lshlrev_b32_e32 v40, 16, v166
	v_and_b32_e32 v41, 0xffff0000, v166
	v_lshlrev_b32_e32 v38, 16, v167
	v_and_b32_e32 v39, 0xffff0000, v167
	v_mul_f32_e32 v42, 0xbfb8aa3b, v40
	v_mul_f32_e32 v43, 0xbfb8aa3b, v41
	v_mul_f32_e32 v44, 0xbfb8aa3b, v38
	v_mul_f32_e32 v45, 0xbfb8aa3b, v39
	v_exp_f32_e32 v42, v42
	v_exp_f32_e32 v43, v43
	v_exp_f32_e32 v44, v44
	v_exp_f32_e32 v45, v45
	v_add_f32_e32 v42, 1.0, v42
	v_add_f32_e32 v43, 1.0, v43
	v_add_f32_e32 v44, 1.0, v44
	v_add_f32_e32 v45, 1.0, v45
	v_rcp_f32_e32 v42, v42
	v_rcp_f32_e32 v43, v43
	v_rcp_f32_e32 v44, v44
	v_rcp_f32_e32 v45, v45
	v_pk_mul_f32 v[40:41], v[42:43], v[40:41]
	s_nop 0
	v_pk_mul_f32 v[32:33], v[32:33], v[40:41]
	v_pk_mul_f32 v[38:39], v[44:45], v[38:39]
	v_cvt_pk_bf16_f32 v32, v32, v33
	v_pk_mul_f32 v[34:35], v[34:35], v[38:39]
	s_nop 0
	v_cvt_pk_bf16_f32 v33, v34, v35
	global_store_dwordx2 v[66:67], v[32:33], off offset:1760
	ds_bpermute_b32 v32, v69, v224
	s_waitcnt lgkmcnt(0)
	v_add_f32_e32 v34, v224, v32
	ds_bpermute_b32 v35, v72, v34
	v_lshlrev_b64 v[32:33], 12, v[64:65]
	v_lshl_add_u64 v[32:33], s[18:19], 0, v[32:33]
	v_lshl_add_u64 v[32:33], v[32:33], 0, s[0:1]
	v_lshl_add_u64 v[32:33], v[32:33], 0, v[136:137]
	s_waitcnt lgkmcnt(0)
	v_add_f32_e32 v34, v34, v35
	v_rcp_f32_e32 v34, v34
	s_mov_b64 s[0:1], 0
	s_waitcnt vmcnt(15)
	v_lshlrev_b32_e32 v40, 16, v168
	v_and_b32_e32 v41, 0xffff0000, v168
	v_lshlrev_b32_e32 v38, 16, v169
	v_and_b32_e32 v39, 0xffff0000, v169
	v_mul_f32_e32 v35, 0xbfb8aa3b, v40
	v_mul_f32_e32 v42, 0xbfb8aa3b, v41
	v_mul_f32_e32 v43, 0xbfb8aa3b, v38
	v_mul_f32_e32 v44, 0xbfb8aa3b, v39
	v_exp_f32_e32 v35, v35
	v_exp_f32_e32 v42, v42
	v_exp_f32_e32 v43, v43
	v_exp_f32_e32 v44, v44
	v_add_f32_e32 v35, 1.0, v35
	v_add_f32_e32 v45, 1.0, v42
	v_add_f32_e32 v46, 1.0, v43
	v_add_f32_e32 v47, 1.0, v44
	v_rcp_f32_e32 v42, v35
	v_rcp_f32_e32 v43, v45
	v_rcp_f32_e32 v44, v46
	v_rcp_f32_e32 v45, v47
	v_pk_mul_f32 v[28:29], v[28:29], v[34:35] op_sel_hi:[1,0]
	v_pk_mul_f32 v[30:31], v[30:31], v[34:35] op_sel_hi:[1,0]
	v_pk_mul_f32 v[40:41], v[42:43], v[40:41]
	v_pk_mul_f32 v[38:39], v[44:45], v[38:39]
	v_pk_mul_f32 v[28:29], v[28:29], v[40:41]
	v_pk_mul_f32 v[30:31], v[30:31], v[38:39]
	v_cvt_pk_bf16_f32 v28, v28, v29
	v_cvt_pk_bf16_f32 v29, v30, v31
	global_store_dwordx2 v[32:33], v[28:29], off offset:1536
	s_waitcnt vmcnt(15)
; __device__ __forceinline__ unsigned cvt_pk_bf16(float lo, float hi) { const f32x2 f = {lo, hi}; const bf16x2_t v = __builtin_convertvector(f, bf16x2_t); return __builtin_bit_cast(unsigned, v); }
; __device__ __forceinline__ float bflo(unsigned u) { return __uint_as_float(u << 16); }
; __device__ __forceinline__ float bfhi(unsigned u) { return __uint_as_float(u & 0xffff0000u); }
; __device__ __forceinline__ float rcp_f(float v) { return __builtin_amdgcn_rcpf(v); }
; __device__ __forceinline__ float silu_f(float v) { return v * rcp_f(1.f + __expf(-v)); }
; __device__ __forceinline__ void b_item(const Params& P, int layer, LAS unsigned char* lds, int item, int tid) {
;     ...
;     for (int u = 0; u < 2; ++u) {
;         float l = lrun[u]; l += __shfl_xor(l, 16); l += __shfl_xor(l, 32);
;         const float inv = rcp_f(l);
;         const size_t tok = tok0 + 64 * qc + 32 * th + 16 * u + c15;
;         const bf16_t* gate = pjp(proj, BG, 128, h, tok);
;         bf16_t* y = (bf16_t*)(P.ws + (layer == 0 ? WS_H : WS_D1)) + tok * DM + YB + h * 128;
; #pragma unroll
;         for (int vb = 0; vb < 8; ++vb) { const int v0 = 16 * vb + 4 * g; const u32x2 gt2 = *(const u32x2*)(gate + v0);
;             u32x2 o; o.x = cvt_pk_bf16(acco[u][vb][0] * inv * silu_f(bflo(gt2.x)), acco[u][vb][1] * inv * silu_f(bfhi(gt2.x)));
;             o.y = cvt_pk_bf16(acco[u][vb][2] * inv * silu_f(bflo(gt2.y)), acco[u][vb][3] * inv * silu_f(bfhi(gt2.y)));
;             *(u32x2*)(y + v0) = o; }
	v_lshlrev_b32_e32 v30, 16, v170
	v_and_b32_e32 v31, 0xffff0000, v170
	v_lshlrev_b32_e32 v28, 16, v171
	v_and_b32_e32 v29, 0xffff0000, v171
	v_mul_f32_e32 v35, 0xbfb8aa3b, v30
	v_mul_f32_e32 v38, 0xbfb8aa3b, v31
	v_mul_f32_e32 v39, 0xbfb8aa3b, v28
	v_mul_f32_e32 v40, 0xbfb8aa3b, v29
	v_exp_f32_e32 v35, v35
	v_exp_f32_e32 v38, v38
	v_exp_f32_e32 v39, v39
	v_exp_f32_e32 v40, v40
	v_add_f32_e32 v35, 1.0, v35
	v_add_f32_e32 v41, 1.0, v38
	v_add_f32_e32 v42, 1.0, v39
	v_add_f32_e32 v43, 1.0, v40
	v_rcp_f32_e32 v38, v35
	v_rcp_f32_e32 v39, v41
	v_rcp_f32_e32 v40, v42
	v_rcp_f32_e32 v41, v43
	v_pk_mul_f32 v[24:25], v[24:25], v[34:35] op_sel_hi:[1,0]
	v_pk_mul_f32 v[26:27], v[26:27], v[34:35] op_sel_hi:[1,0]
	v_pk_mul_f32 v[30:31], v[38:39], v[30:31]
	v_pk_mul_f32 v[28:29], v[40:41], v[28:29]
	v_pk_mul_f32 v[24:25], v[24:25], v[30:31]
	v_pk_mul_f32 v[26:27], v[26:27], v[28:29]
	v_cvt_pk_bf16_f32 v24, v24, v25
	v_cvt_pk_bf16_f32 v25, v26, v27
	global_store_dwordx2 v[32:33], v[24:25], off offset:1568
	v_pk_mul_f32 v[20:21], v[20:21], v[34:35] op_sel_hi:[1,0]
	v_pk_mul_f32 v[22:23], v[22:23], v[34:35] op_sel_hi:[1,0]
	v_pk_mul_f32 v[16:17], v[16:17], v[34:35] op_sel_hi:[1,0]
	v_pk_mul_f32 v[18:19], v[18:19], v[34:35] op_sel_hi:[1,0]
	v_pk_mul_f32 v[12:13], v[12:13], v[34:35] op_sel_hi:[1,0]
	v_pk_mul_f32 v[14:15], v[14:15], v[34:35] op_sel_hi:[1,0]
	v_pk_mul_f32 v[8:9], v[8:9], v[34:35] op_sel_hi:[1,0]
	v_pk_mul_f32 v[10:11], v[10:11], v[34:35] op_sel_hi:[1,0]
	v_pk_mul_f32 v[4:5], v[4:5], v[34:35] op_sel_hi:[1,0]
	v_pk_mul_f32 v[6:7], v[6:7], v[34:35] op_sel_hi:[1,0]
	v_pk_mul_f32 v[0:1], v[0:1], v[34:35] op_sel_hi:[1,0]
	v_pk_mul_f32 v[2:3], v[2:3], v[34:35] op_sel_hi:[1,0]
	s_waitcnt vmcnt(15)
	v_lshlrev_b32_e32 v26, 16, v172
	v_and_b32_e32 v27, 0xffff0000, v172
	v_lshlrev_b32_e32 v24, 16, v173
	v_and_b32_e32 v25, 0xffff0000, v173
	v_mul_f32_e32 v28, 0xbfb8aa3b, v26
	v_mul_f32_e32 v29, 0xbfb8aa3b, v27
	v_mul_f32_e32 v30, 0xbfb8aa3b, v24
	v_mul_f32_e32 v31, 0xbfb8aa3b, v25
	v_exp_f32_e32 v28, v28
	v_exp_f32_e32 v29, v29
	v_exp_f32_e32 v30, v30
	v_exp_f32_e32 v31, v31
	v_add_f32_e32 v28, 1.0, v28
	v_add_f32_e32 v29, 1.0, v29
	v_add_f32_e32 v30, 1.0, v30
	v_add_f32_e32 v31, 1.0, v31
	v_rcp_f32_e32 v28, v28
	v_rcp_f32_e32 v29, v29
	v_rcp_f32_e32 v30, v30
	v_rcp_f32_e32 v31, v31
	v_pk_mul_f32 v[26:27], v[28:29], v[26:27]
	s_nop 0
	v_pk_mul_f32 v[20:21], v[20:21], v[26:27]
	v_pk_mul_f32 v[24:25], v[30:31], v[24:25]
	v_cvt_pk_bf16_f32 v20, v20, v21
	v_pk_mul_f32 v[22:23], v[22:23], v[24:25]
	s_nop 0
	v_cvt_pk_bf16_f32 v21, v22, v23
	global_store_dwordx2 v[32:33], v[20:21], off offset:1600
	s_waitcnt vmcnt(15)
	v_lshlrev_b32_e32 v22, 16, v174
	v_and_b32_e32 v23, 0xffff0000, v174
	v_lshlrev_b32_e32 v20, 16, v175
	v_and_b32_e32 v21, 0xffff0000, v175
	v_mul_f32_e32 v24, 0xbfb8aa3b, v22
	v_mul_f32_e32 v25, 0xbfb8aa3b, v23
	v_mul_f32_e32 v26, 0xbfb8aa3b, v20
	v_mul_f32_e32 v27, 0xbfb8aa3b, v21
	v_exp_f32_e32 v24, v24
	v_exp_f32_e32 v25, v25
	v_exp_f32_e32 v26, v26
	v_exp_f32_e32 v27, v27
	v_add_f32_e32 v24, 1.0, v24
	v_add_f32_e32 v25, 1.0, v25
	v_add_f32_e32 v26, 1.0, v26
	v_add_f32_e32 v27, 1.0, v27
	v_rcp_f32_e32 v24, v24
	v_rcp_f32_e32 v25, v25
	v_rcp_f32_e32 v26, v26
	v_rcp_f32_e32 v27, v27
	v_pk_mul_f32 v[22:23], v[24:25], v[22:23]
	s_nop 0
	v_pk_mul_f32 v[16:17], v[16:17], v[22:23]
	v_pk_mul_f32 v[20:21], v[26:27], v[20:21]
	v_cvt_pk_bf16_f32 v16, v16, v17
	v_pk_mul_f32 v[18:19], v[18:19], v[20:21]
	s_nop 0
	v_cvt_pk_bf16_f32 v17, v18, v19
	global_store_dwordx2 v[32:33], v[16:17], off offset:1632
	s_waitcnt vmcnt(15)
; __device__ __forceinline__ unsigned cvt_pk_bf16(float lo, float hi) { const f32x2 f = {lo, hi}; const bf16x2_t v = __builtin_convertvector(f, bf16x2_t); return __builtin_bit_cast(unsigned, v); }
; __device__ __forceinline__ float bflo(unsigned u) { return __uint_as_float(u << 16); }
; __device__ __forceinline__ float bfhi(unsigned u) { return __uint_as_float(u & 0xffff0000u); }
; __device__ __forceinline__ float rcp_f(float v) { return __builtin_amdgcn_rcpf(v); }
; __device__ __forceinline__ float silu_f(float v) { return v * rcp_f(1.f + __expf(-v)); }
; __device__ __forceinline__ void b_item(const Params& P, int layer, LAS unsigned char* lds, int item, int tid) {
;     ...
;     for (int u = 0; u < 2; ++u) {
;         float l = lrun[u]; l += __shfl_xor(l, 16); l += __shfl_xor(l, 32);
;         const float inv = rcp_f(l);
;         const size_t tok = tok0 + 64 * qc + 32 * th + 16 * u + c15;
;         const bf16_t* gate = pjp(proj, BG, 128, h, tok);
;         bf16_t* y = (bf16_t*)(P.ws + (layer == 0 ? WS_H : WS_D1)) + tok * DM + YB + h * 128;
; #pragma unroll
;         for (int vb = 0; vb < 8; ++vb) { const int v0 = 16 * vb + 4 * g; const u32x2 gt2 = *(const u32x2*)(gate + v0);
;             u32x2 o; o.x = cvt_pk_bf16(acco[u][vb][0] * inv * silu_f(bflo(gt2.x)), acco[u][vb][1] * inv * silu_f(bfhi(gt2.x)));
;             o.y = cvt_pk_bf16(acco[u][vb][2] * inv * silu_f(bflo(gt2.y)), acco[u][vb][3] * inv * silu_f(bfhi(gt2.y)));
;             *(u32x2*)(y + v0) = o; }
	v_lshlrev_b32_e32 v18, 16, v228
	v_and_b32_e32 v19, 0xffff0000, v228
	v_lshlrev_b32_e32 v16, 16, v229
	v_and_b32_e32 v17, 0xffff0000, v229
	v_mul_f32_e32 v20, 0xbfb8aa3b, v18
	v_mul_f32_e32 v21, 0xbfb8aa3b, v19
	v_mul_f32_e32 v22, 0xbfb8aa3b, v16
	v_mul_f32_e32 v23, 0xbfb8aa3b, v17
	v_exp_f32_e32 v20, v20
	v_exp_f32_e32 v21, v21
	v_exp_f32_e32 v22, v22
	v_exp_f32_e32 v23, v23
	v_add_f32_e32 v20, 1.0, v20
	v_add_f32_e32 v21, 1.0, v21
	v_add_f32_e32 v22, 1.0, v22
	v_add_f32_e32 v23, 1.0, v23
	v_rcp_f32_e32 v20, v20
	v_rcp_f32_e32 v21, v21
	v_rcp_f32_e32 v22, v22
	v_rcp_f32_e32 v23, v23
	v_pk_mul_f32 v[18:19], v[20:21], v[18:19]
	s_nop 0
	v_pk_mul_f32 v[12:13], v[12:13], v[18:19]
	v_pk_mul_f32 v[16:17], v[22:23], v[16:17]
	v_cvt_pk_bf16_f32 v12, v12, v13
	v_pk_mul_f32 v[14:15], v[14:15], v[16:17]
	s_nop 0
	v_cvt_pk_bf16_f32 v13, v14, v15
	global_store_dwordx2 v[32:33], v[12:13], off offset:1664
	s_waitcnt vmcnt(15)
	v_lshlrev_b32_e32 v14, 16, v230
	v_and_b32_e32 v15, 0xffff0000, v230
	v_lshlrev_b32_e32 v12, 16, v231
	v_and_b32_e32 v13, 0xffff0000, v231
	v_mul_f32_e32 v16, 0xbfb8aa3b, v14
	v_mul_f32_e32 v17, 0xbfb8aa3b, v15
	v_mul_f32_e32 v18, 0xbfb8aa3b, v12
	v_mul_f32_e32 v19, 0xbfb8aa3b, v13
	v_exp_f32_e32 v16, v16
	v_exp_f32_e32 v17, v17
	v_exp_f32_e32 v18, v18
	v_exp_f32_e32 v19, v19
	v_add_f32_e32 v16, 1.0, v16
	v_add_f32_e32 v17, 1.0, v17
	v_add_f32_e32 v18, 1.0, v18
	v_add_f32_e32 v19, 1.0, v19
	v_rcp_f32_e32 v16, v16
	v_rcp_f32_e32 v17, v17
	v_rcp_f32_e32 v18, v18
	v_rcp_f32_e32 v19, v19
	v_pk_mul_f32 v[14:15], v[16:17], v[14:15]
	s_nop 0
	v_pk_mul_f32 v[8:9], v[8:9], v[14:15]
	v_pk_mul_f32 v[12:13], v[18:19], v[12:13]
	v_cvt_pk_bf16_f32 v8, v8, v9
	v_pk_mul_f32 v[10:11], v[10:11], v[12:13]
	s_nop 0
	v_cvt_pk_bf16_f32 v9, v10, v11
	global_store_dwordx2 v[32:33], v[8:9], off offset:1696
	s_waitcnt vmcnt(15)
	v_lshlrev_b32_e32 v10, 16, v226
	v_and_b32_e32 v11, 0xffff0000, v226
	v_lshlrev_b32_e32 v8, 16, v227
	v_and_b32_e32 v9, 0xffff0000, v227
	v_mul_f32_e32 v12, 0xbfb8aa3b, v10
	v_mul_f32_e32 v13, 0xbfb8aa3b, v11
	v_mul_f32_e32 v14, 0xbfb8aa3b, v8
	v_mul_f32_e32 v15, 0xbfb8aa3b, v9
	v_exp_f32_e32 v12, v12
	v_exp_f32_e32 v13, v13
	v_exp_f32_e32 v14, v14
	v_exp_f32_e32 v15, v15
	v_add_f32_e32 v12, 1.0, v12
	v_add_f32_e32 v13, 1.0, v13
	v_add_f32_e32 v14, 1.0, v14
	v_add_f32_e32 v15, 1.0, v15
	v_rcp_f32_e32 v12, v12
	v_rcp_f32_e32 v13, v13
	v_rcp_f32_e32 v14, v14
	v_rcp_f32_e32 v15, v15
	v_pk_mul_f32 v[10:11], v[12:13], v[10:11]
	s_nop 0
	v_pk_mul_f32 v[4:5], v[4:5], v[10:11]
	v_pk_mul_f32 v[8:9], v[14:15], v[8:9]
	v_cvt_pk_bf16_f32 v4, v4, v5
	v_pk_mul_f32 v[6:7], v[6:7], v[8:9]
	s_nop 0
	v_cvt_pk_bf16_f32 v5, v6, v7
	global_store_dwordx2 v[32:33], v[4:5], off offset:1728
	s_waitcnt vmcnt(15)
	v_lshlrev_b32_e32 v6, 16, v162
	v_and_b32_e32 v7, 0xffff0000, v162
	v_lshlrev_b32_e32 v4, 16, v163
	v_and_b32_e32 v5, 0xffff0000, v163
	v_mul_f32_e32 v8, 0xbfb8aa3b, v6
	v_mul_f32_e32 v9, 0xbfb8aa3b, v7
	v_mul_f32_e32 v10, 0xbfb8aa3b, v4
	v_mul_f32_e32 v11, 0xbfb8aa3b, v5
	v_exp_f32_e32 v8, v8
	v_exp_f32_e32 v9, v9
	v_exp_f32_e32 v10, v10
	v_exp_f32_e32 v11, v11
	v_add_f32_e32 v8, 1.0, v8
	v_add_f32_e32 v9, 1.0, v9
	v_add_f32_e32 v10, 1.0, v10
	v_add_f32_e32 v11, 1.0, v11
	v_rcp_f32_e32 v8, v8
	v_rcp_f32_e32 v9, v9
	v_rcp_f32_e32 v10, v10
	v_rcp_f32_e32 v11, v11
	v_pk_mul_f32 v[6:7], v[8:9], v[6:7]
	s_nop 0
	v_pk_mul_f32 v[0:1], v[0:1], v[6:7]
	v_pk_mul_f32 v[4:5], v[10:11], v[4:5]
	v_cvt_pk_bf16_f32 v0, v0, v1
	v_pk_mul_f32 v[2:3], v[2:3], v[4:5]
	s_nop 0
	v_cvt_pk_bf16_f32 v1, v2, v3
	global_store_dwordx2 v[32:33], v[0:1], off offset:1760

; #define LAS __attribute__((address_space(3)))
; __global__ __launch_bounds__(512, 2) void hybrid_fwd(Params P0) {
;     ...
;                 unsigned* ctr = (unsigned*)(P.ws + WS_END) + 3584 + layer; LAS int* sit = (LAS int*)(lds + 132608);
;                 for (;;) {
;                     if (tid == 0) *sit = (int)atomicAdd(ctr, 1u);
;                     __syncthreads();
;                     const int it = *sit;
;                     __syncthreads();
.LBB0_142:
	s_and_saveexec_b64 s[0:1], s[40:41]
	s_cbranch_execz .LBB0_146
	s_waitcnt vmcnt(16)
	v_mov_b32_e32 v1, s79
	ds_write_b32 v1, v246

; __device__ __forceinline__ f32x4 mfma16(bf16x8 a, bf16x8 b, f32x4 c) { return __builtin_amdgcn_mfma_f32_16x16x32_bf16(a, b, c, 0, 0, 0); }
; __device__ __forceinline__ void b_item(const Params& P, int layer, LAS unsigned char* lds, int item, int tid) {
;     ...
;             __builtin_amdgcn_s_setprio(1);
; #pragma unroll
;             for (int kk = 0; kk < 4; ++kk) { const bf16x8 q0 = row_frag_a(Qw, kaddr[kk], 0), q1 = row_frag_a(Qw, kaddr[kk], 1);
; #pragma unroll
;                 for (int sb = 0; sb < 4; ++sb) { const bf16x8 kf = row_frag_a(Kt, kaddr[kk], sb);
;                     accs[0][sb] = mfma16(kf, q0, accs[0][sb]); accs[1][sb] = mfma16(kf, q1, accs[1][sb]); } }
;             __builtin_amdgcn_s_setprio(0);
;             bf16x8 pf[2][2]; float alpha[2];
; #pragma unroll
;             for (int u = 0; u < 2; ++u) { const int t = 32 * th + 16 * u + c15; float mt = -1e30f;
; #pragma unroll
;                 for (int sb = 0; sb < 4; ++sb) {
;                     if (dl >= 192) {
; #pragma unroll
;                         for (int r = 0; r < 4; ++r) { const float xv = accs[u][sb][r] * 0.08838834764831845f + bfar; accs[u][sb][r] = xv; mt = fmaxf(mt, xv); }
;                     } else {
; #pragma unroll
;                         for (int r = 0; r < 4; ++r) { const int s = 16 * sb + 4 * g + r; int rel = t - s + dl; rel = rel > 128 ? 128 : rel;
;                             const float xv = accs[u][sb][r] * 0.08838834764831845f + bias[rel + 128]; accs[u][sb][r] = xv; mt = fmaxf(mt, xv); } } }
.LBB0_163:
	s_add_i32 s57, s57, 1
	v_cmp_ge_i32_e32 vcc, s57, v191
	v_cmp_le_i32_e64 s[0:1], s57, v207
	s_and_b64 s[0:1], vcc, s[0:1]
	s_and_saveexec_b64 s[14:15], s[0:1]
	s_cbranch_execz .LBB0_160
	s_add_i32 s28, s28, 0
	s_add_i32 s28, s28, 0x10000
	s_setprio 1
	v_add_u32_e32 v244, v206, v193
	v_add_u32_e32 v245, s28, v193
	ds_read_b128 v[164:167], v244
	ds_read_b128 v[168:171], v244 offset:4096
	ds_read_b128 v[236:239], v245
	ds_read_b128 v[240:243], v245 offset:4096
	ds_read_b128 v[252:255], v245 offset:8192
	s_waitcnt lgkmcnt(2)
	v_mfma_f32_16x16x32_bf16 v[92:95], v[236:239], v[164:167], 0
	v_mfma_f32_16x16x32_bf16 v[76:79], v[236:239], v[168:171], 0
	ds_read_b128 v[236:239], v245 offset:12288
	v_add_u32_e32 v244, v206, v194
	ds_read_b128 v[172:175], v244
	ds_read_b128 v[228:231], v244 offset:4096
	s_waitcnt lgkmcnt(4)
	v_mfma_f32_16x16x32_bf16 v[88:91], v[240:243], v[164:167], 0
	v_mfma_f32_16x16x32_bf16 v[72:75], v[240:243], v[168:171], 0
	v_add_u32_e32 v245, s28, v194
	ds_read_b128 v[240:243], v245
	s_waitcnt lgkmcnt(4)
	v_mfma_f32_16x16x32_bf16 v[84:87], v[252:255], v[164:167], 0
	v_mfma_f32_16x16x32_bf16 v[68:71], v[252:255], v[168:171], 0
	ds_read_b128 v[252:255], v245 offset:4096
	s_waitcnt lgkmcnt(4)
	v_mfma_f32_16x16x32_bf16 v[80:83], v[236:239], v[164:167], 0
	v_mfma_f32_16x16x32_bf16 v[64:67], v[236:239], v[168:171], 0
	ds_read_b128 v[236:239], v245 offset:8192
	s_waitcnt lgkmcnt(2)
	v_mfma_f32_16x16x32_bf16 v[92:95], v[240:243], v[172:175], v[92:95]
	v_mfma_f32_16x16x32_bf16 v[76:79], v[240:243], v[228:231], v[76:79]
	ds_read_b128 v[240:243], v245 offset:12288
	v_add_u32_e32 v244, v206, v195
	ds_read_b128 v[164:167], v244
	ds_read_b128 v[168:171], v244 offset:4096
	s_waitcnt lgkmcnt(4)
	v_mfma_f32_16x16x32_bf16 v[88:91], v[252:255], v[172:175], v[88:91]
	v_mfma_f32_16x16x32_bf16 v[72:75], v[252:255], v[228:231], v[72:75]
	v_add_u32_e32 v245, s28, v195
	ds_read_b128 v[252:255], v245
	s_waitcnt lgkmcnt(4)
	v_mfma_f32_16x16x32_bf16 v[84:87], v[236:239], v[172:175], v[84:87]
	v_mfma_f32_16x16x32_bf16 v[68:71], v[236:239], v[228:231], v[68:71]
	ds_read_b128 v[236:239], v245 offset:4096
	s_waitcnt lgkmcnt(4)
	v_mfma_f32_16x16x32_bf16 v[80:83], v[240:243], v[172:175], v[80:83]
	v_mfma_f32_16x16x32_bf16 v[64:67], v[240:243], v[228:231], v[64:67]
	ds_read_b128 v[240:243], v245 offset:8192
	s_waitcnt lgkmcnt(2)
	v_mfma_f32_16x16x32_bf16 v[92:95], v[252:255], v[164:167], v[92:95]
	v_mfma_f32_16x16x32_bf16 v[76:79], v[252:255], v[168:171], v[76:79]
	ds_read_b128 v[252:255], v245 offset:12288
	v_add_u32_e32 v244, v206, v196
	ds_read_b128 v[172:175], v244
	ds_read_b128 v[228:231], v244 offset:4096
	s_waitcnt lgkmcnt(4)
	v_mfma_f32_16x16x32_bf16 v[88:91], v[236:239], v[164:167], v[88:91]
	v_mfma_f32_16x16x32_bf16 v[72:75], v[236:239], v[168:171], v[72:75]
	v_add_u32_e32 v245, s28, v196
	ds_read_b128 v[236:239], v245
	s_waitcnt lgkmcnt(4)
	v_mfma_f32_16x16x32_bf16 v[84:87], v[240:243], v[164:167], v[84:87]
	v_mfma_f32_16x16x32_bf16 v[68:71], v[240:243], v[168:171], v[68:71]
	ds_read_b128 v[240:243], v245 offset:4096
	s_waitcnt lgkmcnt(4)
	v_mfma_f32_16x16x32_bf16 v[80:83], v[252:255], v[164:167], v[80:83]
	v_mfma_f32_16x16x32_bf16 v[64:67], v[252:255], v[168:171], v[64:67]
	ds_read_b128 v[252:255], v245 offset:8192
	s_waitcnt lgkmcnt(2)
	v_mfma_f32_16x16x32_bf16 v[92:95], v[236:239], v[172:175], v[92:95]
	v_mfma_f32_16x16x32_bf16 v[76:79], v[236:239], v[228:231], v[76:79]
	ds_read_b128 v[236:239], v245 offset:12288
	s_waitcnt lgkmcnt(2)
	v_mfma_f32_16x16x32_bf16 v[88:91], v[240:243], v[172:175], v[88:91]
	v_mfma_f32_16x16x32_bf16 v[72:75], v[240:243], v[228:231], v[72:75]
	s_waitcnt lgkmcnt(1)
	v_mfma_f32_16x16x32_bf16 v[84:87], v[252:255], v[172:175], v[84:87]
	v_mfma_f32_16x16x32_bf16 v[68:71], v[252:255], v[228:231], v[68:71]
	s_waitcnt lgkmcnt(0)
	v_mfma_f32_16x16x32_bf16 v[80:83], v[236:239], v[172:175], v[80:83]
	v_mfma_f32_16x16x32_bf16 v[64:67], v[236:239], v[228:231], v[64:67]
	s_setprio 0
	v_cmp_gt_i32_e32 vcc, 3, v221
	v_add_u32_e32 v172, v192, v222
	s_and_saveexec_b64 s[0:1], vcc
	s_xor_b64 s[0:1], exec, s[0:1]
	s_cbranch_execz .LBB0_166
	v_add_u32_e32 v166, 0x200, v172
	v_add_u32_e32 v165, 0x1ff, v172
	v_min_i32_e32 v164, 0x80, v166
	v_min_i32_e32 v165, 0x80, v165
	v_lshl_add_u32 v164, v164, 2, s74
	v_lshl_add_u32 v165, v165, 2, s74
	ds_read_b32 v164, v164 offset:512
	ds_read_b32 v165, v165 offset:512
	v_min_i32_e32 v244, 0x82, v166
	v_min_i32_e32 v245, 0x83, v166
	v_lshl_add_u32 v244, v244, 2, s74
	v_lshl_add_u32 v245, v245, 2, s74
	ds_read_b32 v244, v244 offset:504
	ds_read_b32 v245, v245 offset:500
	s_waitcnt lgkmcnt(2)
	v_pk_fma_f32 v[164:165], v[92:93], s[34:35], v[164:165] op_sel_hi:[1,0,1]
	v_max3_f32 v168, v164, s96, v165
	s_waitcnt lgkmcnt(0)
	v_pk_fma_f32 v[166:167], v[94:95], s[34:35], v[244:245] op_sel_hi:[1,0,1]
	s_nop 0
	v_max3_f32 v169, v168, v166, v167
.LBB0_166:
	s_andn2_saveexec_b64 s[0:1], s[0:1]
	v_pk_fma_f32 v[164:165], v[92:93], s[34:35], v[162:163] op_sel_hi:[1,0,1]
	v_pk_fma_f32 v[166:167], v[94:95], s[34:35], v[162:163] op_sel_hi:[1,0,1]
	v_max3_f32 v92, v164, s96, v165
	v_max3_f32 v169, v92, v166, v167
	s_or_b64 exec, exec, s[0:1]
	v_add_u32_e32 v174, v192, v223
	s_and_saveexec_b64 s[0:1], vcc
	s_xor_b64 s[0:1], exec, s[0:1]
	s_cbranch_execz .LBB0_170
	v_add_u32_e32 v92, 0x1f0, v174
	v_add_u32_e32 v93, 0x1ef, v174
	v_min_i32_e32 v92, 0x80, v92
	v_min_i32_e32 v93, 0x80, v93
	v_lshl_add_u32 v92, v92, 2, s74
	v_lshl_add_u32 v93, v93, 2, s74
	ds_read_b32 v92, v92 offset:512
	ds_read_b32 v93, v93 offset:512
	v_add_u32_e32 v244, 0x1ee, v174
	v_add_u32_e32 v245, 0x1ed, v174
	v_min_i32_e32 v244, 0x80, v244
	v_min_i32_e32 v245, 0x80, v245
	v_lshl_add_u32 v244, v244, 2, s74
	v_lshl_add_u32 v245, v245, 2, s74
	ds_read_b32 v244, v244 offset:512
	ds_read_b32 v245, v245 offset:512
	s_waitcnt lgkmcnt(2)
	v_pk_fma_f32 v[92:93], v[88:89], s[34:35], v[92:93] op_sel_hi:[1,0,1]
	v_max3_f32 v168, v169, v92, v93
	s_waitcnt lgkmcnt(0)
	v_pk_fma_f32 v[94:95], v[90:91], s[34:35], v[244:245] op_sel_hi:[1,0,1]
	s_nop 0
	v_max3_f32 v168, v168, v94, v95
	s_andn2_saveexec_b64 s[0:1], s[0:1]
	s_branch .LBB0_171

; __device__ __forceinline__ void b_item(const Params& P, int layer, LAS unsigned char* lds, int item, int tid) {
;     ...
;             for (int u = 0; u < 2; ++u) { const int t = 32 * th + 16 * u + c15; float mt = -1e30f;
; #pragma unroll
;                 for (int sb = 0; sb < 4; ++sb) {
;                     if (dl >= 192) {
; #pragma unroll
;                         for (int r = 0; r < 4; ++r) { const float xv = accs[u][sb][r] * 0.08838834764831845f + bfar; accs[u][sb][r] = xv; mt = fmaxf(mt, xv); }
;                     } else {
; #pragma unroll
;                         for (int r = 0; r < 4; ++r) { const int s = 16 * sb + 4 * g + r; int rel = t - s + dl; rel = rel > 128 ? 128 : rel;
;                             const float xv = accs[u][sb][r] * 0.08838834764831845f + bias[rel + 128]; accs[u][sb][r] = xv; mt = fmaxf(mt, xv); } } }
.LBB0_171:
	v_pk_fma_f32 v[92:93], v[88:89], s[34:35], v[162:163] op_sel_hi:[1,0,1]
	v_pk_fma_f32 v[94:95], v[90:91], s[34:35], v[162:163] op_sel_hi:[1,0,1]
	v_max3_f32 v88, v169, v92, v93
	v_max3_f32 v168, v88, v94, v95
	s_or_b64 exec, exec, s[0:1]
	s_and_saveexec_b64 s[0:1], vcc
	s_xor_b64 s[0:1], exec, s[0:1]
	s_cbranch_execz .LBB0_174
	v_add_u32_e32 v88, 0x1e0, v174
	v_add_u32_e32 v89, 0x1df, v174
	v_min_i32_e32 v88, 0x80, v88
	v_min_i32_e32 v89, 0x80, v89
	v_lshl_add_u32 v88, v88, 2, s74
	v_lshl_add_u32 v89, v89, 2, s74
	ds_read_b32 v88, v88 offset:512
	ds_read_b32 v89, v89 offset:512
	v_add_u32_e32 v244, 0x1de, v174
	v_add_u32_e32 v245, 0x1dd, v174
	v_min_i32_e32 v244, 0x80, v244
	v_min_i32_e32 v245, 0x80, v245
	v_lshl_add_u32 v244, v244, 2, s74
	v_lshl_add_u32 v245, v245, 2, s74
	ds_read_b32 v244, v244 offset:512
	ds_read_b32 v245, v245 offset:512
	s_waitcnt lgkmcnt(2)
	v_pk_fma_f32 v[88:89], v[84:85], s[34:35], v[88:89] op_sel_hi:[1,0,1]
	v_max3_f32 v168, v168, v88, v89
	s_waitcnt lgkmcnt(0)
	v_pk_fma_f32 v[90:91], v[86:87], s[34:35], v[244:245] op_sel_hi:[1,0,1]
	s_nop 0
	v_max3_f32 v169, v168, v90, v91
	s_andn2_saveexec_b64 s[0:1], s[0:1]
	s_branch .LBB0_175

; __device__ __forceinline__ void b_item(const Params& P, int layer, LAS unsigned char* lds, int item, int tid) {
;     ...
;             for (int u = 0; u < 2; ++u) { const int t = 32 * th + 16 * u + c15; float mt = -1e30f;
; #pragma unroll
;                 for (int sb = 0; sb < 4; ++sb) {
;                     if (dl >= 192) {
; #pragma unroll
;                         for (int r = 0; r < 4; ++r) { const float xv = accs[u][sb][r] * 0.08838834764831845f + bfar; accs[u][sb][r] = xv; mt = fmaxf(mt, xv); }
;                     } else {
; #pragma unroll
;                         for (int r = 0; r < 4; ++r) { const int s = 16 * sb + 4 * g + r; int rel = t - s + dl; rel = rel > 128 ? 128 : rel;
;                             const float xv = accs[u][sb][r] * 0.08838834764831845f + bias[rel + 128]; accs[u][sb][r] = xv; mt = fmaxf(mt, xv); } } }
.LBB0_175:
	v_pk_fma_f32 v[88:89], v[84:85], s[34:35], v[162:163] op_sel_hi:[1,0,1]
	v_pk_fma_f32 v[90:91], v[86:87], s[34:35], v[162:163] op_sel_hi:[1,0,1]
	v_max3_f32 v84, v168, v88, v89
	v_max3_f32 v169, v84, v90, v91
	s_or_b64 exec, exec, s[0:1]
	s_and_saveexec_b64 s[0:1], vcc
	s_xor_b64 s[0:1], exec, s[0:1]
	s_cbranch_execz .LBB0_178
	v_add_u32_e32 v84, 0x1d0, v174
	v_add_u32_e32 v85, 0x1cf, v174
	v_min_i32_e32 v84, 0x80, v84
	v_min_i32_e32 v85, 0x80, v85
	v_lshl_add_u32 v84, v84, 2, s74
	v_lshl_add_u32 v85, v85, 2, s74
	ds_read_b32 v84, v84 offset:512
	ds_read_b32 v85, v85 offset:512
	v_add_u32_e32 v244, 0x1ce, v174
	v_add_u32_e32 v245, 0x1cd, v174
	v_min_i32_e32 v244, 0x80, v244
	v_min_i32_e32 v245, 0x80, v245
	v_lshl_add_u32 v244, v244, 2, s74
	v_lshl_add_u32 v245, v245, 2, s74
	ds_read_b32 v244, v244 offset:512
	ds_read_b32 v245, v245 offset:512
	s_waitcnt lgkmcnt(2)
	v_pk_fma_f32 v[84:85], v[80:81], s[34:35], v[84:85] op_sel_hi:[1,0,1]
	v_max3_f32 v168, v169, v84, v85
	s_waitcnt lgkmcnt(0)
	v_pk_fma_f32 v[86:87], v[82:83], s[34:35], v[244:245] op_sel_hi:[1,0,1]
	s_nop 0
	v_max3_f32 v168, v168, v86, v87
	s_andn2_saveexec_b64 s[0:1], s[0:1]
	s_cbranch_execnz .LBB0_179
	s_branch .LBB0_180

; __device__ __forceinline__ void b_item(const Params& P, int layer, LAS unsigned char* lds, int item, int tid) {
;     ...
;             for (int u = 0; u < 2; ++u) { const int t = 32 * th + 16 * u + c15; float mt = -1e30f;
; #pragma unroll
;                 for (int sb = 0; sb < 4; ++sb) {
;                     if (dl >= 192) {
; #pragma unroll
;                         for (int r = 0; r < 4; ++r) { const float xv = accs[u][sb][r] * 0.08838834764831845f + bfar; accs[u][sb][r] = xv; mt = fmaxf(mt, xv); }
;                     } else {
; #pragma unroll
;                         for (int r = 0; r < 4; ++r) { const int s = 16 * sb + 4 * g + r; int rel = t - s + dl; rel = rel > 128 ? 128 : rel;
;                             const float xv = accs[u][sb][r] * 0.08838834764831845f + bias[rel + 128]; accs[u][sb][r] = xv; mt = fmaxf(mt, xv); } } }
;                 mt = fmaxf(mt, __shfl_xor(mt, 16)); mt = fmaxf(mt, __shfl_xor(mt, 32));
.LBB0_180:
	s_or_b64 exec, exec, s[0:1]
	v_and_b32_e32 v81, 64, v184
	v_xor_b32_e32 v80, 16, v184
	v_add_u32_e32 v81, 64, v81
	v_cmp_lt_i32_e64 s[0:1], v80, v81
	v_xor_b32_e32 v83, 32, v184
	s_nop 0
	v_cndmask_b32_e64 v80, v184, v80, s[0:1]
	v_lshlrev_b32_e32 v82, 2, v80
	ds_bpermute_b32 v80, v82, v168
	v_cmp_lt_i32_e64 s[0:1], v83, v81
	s_waitcnt lgkmcnt(0)
	v_max_f32_e32 v80, v80, v80
	v_cndmask_b32_e64 v81, v184, v83, s[0:1]
	v_lshlrev_b32_e32 v228, 2, v81
	v_max_f32_e32 v81, v168, v168
	v_max_f32_e32 v80, v81, v80
	ds_bpermute_b32 v81, v228, v80
	s_and_saveexec_b64 s[0:1], vcc
	s_xor_b64 s[0:1], exec, s[0:1]
	s_cbranch_execz .LBB0_182
	v_add_u32_e32 v83, 0x210, v172
	v_add_u32_e32 v169, 0x20f, v172
	v_min_i32_e32 v168, 0x80, v83
	v_min_i32_e32 v169, 0x80, v169
	v_lshl_add_u32 v168, v168, 2, s74
	v_lshl_add_u32 v169, v169, 2, s74
	ds_read_b32 v168, v168 offset:512
	ds_read_b32 v169, v169 offset:512
	v_min_i32_e32 v244, 0x82, v83
	v_min_i32_e32 v245, 0x83, v83
	v_lshl_add_u32 v244, v244, 2, s74
	v_lshl_add_u32 v245, v245, 2, s74
	ds_read_b32 v244, v244 offset:504
	ds_read_b32 v245, v245 offset:500
	s_waitcnt lgkmcnt(2)
	v_pk_fma_f32 v[168:169], v[76:77], s[34:35], v[168:169] op_sel_hi:[1,0,1]
	v_max3_f32 v173, v168, s96, v169
	s_waitcnt lgkmcnt(0)
	v_pk_fma_f32 v[170:171], v[78:79], s[34:35], v[244:245] op_sel_hi:[1,0,1]
	s_nop 0
	v_max3_f32 v173, v173, v170, v171
	s_andn2_saveexec_b64 s[0:1], s[0:1]
	s_branch .LBB0_183

; __device__ __forceinline__ void b_item(const Params& P, int layer, LAS unsigned char* lds, int item, int tid) {
;     ...
;             for (int u = 0; u < 2; ++u) { const int t = 32 * th + 16 * u + c15; float mt = -1e30f;
; #pragma unroll
;                 for (int sb = 0; sb < 4; ++sb) {
;                     if (dl >= 192) {
; #pragma unroll
;                         for (int r = 0; r < 4; ++r) { const float xv = accs[u][sb][r] * 0.08838834764831845f + bfar; accs[u][sb][r] = xv; mt = fmaxf(mt, xv); }
;                     } else {
; #pragma unroll
;                         for (int r = 0; r < 4; ++r) { const int s = 16 * sb + 4 * g + r; int rel = t - s + dl; rel = rel > 128 ? 128 : rel;
;                             const float xv = accs[u][sb][r] * 0.08838834764831845f + bias[rel + 128]; accs[u][sb][r] = xv; mt = fmaxf(mt, xv); } } }
.LBB0_183:
	v_pk_fma_f32 v[168:169], v[76:77], s[34:35], v[162:163] op_sel_hi:[1,0,1]
	v_pk_fma_f32 v[170:171], v[78:79], s[34:35], v[162:163] op_sel_hi:[1,0,1]
	v_max3_f32 v76, v168, s96, v169
	v_max3_f32 v173, v76, v170, v171
	s_or_b64 exec, exec, s[0:1]
	s_and_saveexec_b64 s[0:1], vcc
	s_xor_b64 s[0:1], exec, s[0:1]
	s_cbranch_execz .LBB0_186
	v_add_u32_e32 v76, 0x200, v172
	v_add_u32_e32 v78, 0x210, v172
	v_min_i32_e32 v76, 0x80, v76
	v_min_i32_e32 v77, 0x91, v78
	v_lshl_add_u32 v76, v76, 2, s74
	v_lshl_add_u32 v77, v77, 2, s74
	ds_read_b32 v76, v76 offset:512
	ds_read_b32 v77, v77 offset:444
	v_min_i32_e32 v244, 0x92, v78
	v_min_i32_e32 v245, 0x93, v78
	v_lshl_add_u32 v244, v244, 2, s74
	v_lshl_add_u32 v245, v245, 2, s74
	ds_read_b32 v244, v244 offset:440
	ds_read_b32 v245, v245 offset:436
	s_waitcnt lgkmcnt(2)
	v_pk_fma_f32 v[76:77], v[72:73], s[34:35], v[76:77] op_sel_hi:[1,0,1]
	v_max3_f32 v83, v173, v76, v77
	s_waitcnt lgkmcnt(0)
	v_pk_fma_f32 v[78:79], v[74:75], s[34:35], v[244:245] op_sel_hi:[1,0,1]
	s_nop 0
	v_max3_f32 v83, v83, v78, v79
	s_andn2_saveexec_b64 s[0:1], s[0:1]
	s_branch .LBB0_187

; __device__ __forceinline__ void b_item(const Params& P, int layer, LAS unsigned char* lds, int item, int tid) {
;     ...
;             for (int u = 0; u < 2; ++u) { const int t = 32 * th + 16 * u + c15; float mt = -1e30f;
; #pragma unroll
;                 for (int sb = 0; sb < 4; ++sb) {
;                     if (dl >= 192) {
; #pragma unroll
;                         for (int r = 0; r < 4; ++r) { const float xv = accs[u][sb][r] * 0.08838834764831845f + bfar; accs[u][sb][r] = xv; mt = fmaxf(mt, xv); }
;                     } else {
; #pragma unroll
;                         for (int r = 0; r < 4; ++r) { const int s = 16 * sb + 4 * g + r; int rel = t - s + dl; rel = rel > 128 ? 128 : rel;
;                             const float xv = accs[u][sb][r] * 0.08838834764831845f + bias[rel + 128]; accs[u][sb][r] = xv; mt = fmaxf(mt, xv); } } }
.LBB0_187:
	v_pk_fma_f32 v[76:77], v[72:73], s[34:35], v[162:163] op_sel_hi:[1,0,1]
	v_pk_fma_f32 v[78:79], v[74:75], s[34:35], v[162:163] op_sel_hi:[1,0,1]
	v_max3_f32 v72, v173, v76, v77
	v_max3_f32 v83, v72, v78, v79
	s_or_b64 exec, exec, s[0:1]
	s_and_saveexec_b64 s[0:1], vcc
	s_xor_b64 s[0:1], exec, s[0:1]
	s_cbranch_execz .LBB0_190
	v_add_u32_e32 v72, 0x1f0, v174
	v_add_u32_e32 v73, 0x1ef, v174
	v_min_i32_e32 v72, 0x80, v72
	v_min_i32_e32 v73, 0x80, v73
	v_lshl_add_u32 v72, v72, 2, s74
	v_lshl_add_u32 v73, v73, 2, s74
	ds_read_b32 v72, v72 offset:512
	ds_read_b32 v73, v73 offset:512
	v_add_u32_e32 v244, 0x1ee, v174
	v_add_u32_e32 v245, 0x1ed, v174
	v_min_i32_e32 v244, 0x80, v244
	v_min_i32_e32 v245, 0x80, v245
	v_lshl_add_u32 v244, v244, 2, s74
	v_lshl_add_u32 v245, v245, 2, s74
	ds_read_b32 v244, v244 offset:512
	ds_read_b32 v245, v245 offset:512
	s_waitcnt lgkmcnt(2)
	v_pk_fma_f32 v[72:73], v[68:69], s[34:35], v[72:73] op_sel_hi:[1,0,1]
	v_max3_f32 v83, v83, v72, v73
	s_waitcnt lgkmcnt(0)
	v_pk_fma_f32 v[74:75], v[70:71], s[34:35], v[244:245] op_sel_hi:[1,0,1]
	s_nop 0
	v_max3_f32 v230, v83, v74, v75
	s_andn2_saveexec_b64 s[0:1], s[0:1]
	s_branch .LBB0_191

; __device__ __forceinline__ void b_item(const Params& P, int layer, LAS unsigned char* lds, int item, int tid) {
;     ...
;             for (int u = 0; u < 2; ++u) { const int t = 32 * th + 16 * u + c15; float mt = -1e30f;
; #pragma unroll
;                 for (int sb = 0; sb < 4; ++sb) {
;                     if (dl >= 192) {
; #pragma unroll
;                         for (int r = 0; r < 4; ++r) { const float xv = accs[u][sb][r] * 0.08838834764831845f + bfar; accs[u][sb][r] = xv; mt = fmaxf(mt, xv); }
;                     } else {
; #pragma unroll
;                         for (int r = 0; r < 4; ++r) { const int s = 16 * sb + 4 * g + r; int rel = t - s + dl; rel = rel > 128 ? 128 : rel;
;                             const float xv = accs[u][sb][r] * 0.08838834764831845f + bias[rel + 128]; accs[u][sb][r] = xv; mt = fmaxf(mt, xv); } } }
.LBB0_191:
	v_pk_fma_f32 v[72:73], v[68:69], s[34:35], v[162:163] op_sel_hi:[1,0,1]
	v_pk_fma_f32 v[74:75], v[70:71], s[34:35], v[162:163] op_sel_hi:[1,0,1]
	v_max3_f32 v68, v83, v72, v73
	v_max3_f32 v230, v68, v74, v75
	s_or_b64 exec, exec, s[0:1]
	s_and_saveexec_b64 s[0:1], vcc
	s_xor_b64 s[0:1], exec, s[0:1]
	s_cbranch_execz .LBB0_194
	v_add_u32_e32 v68, 0x1e0, v174
	v_add_u32_e32 v69, 0x1df, v174
	v_min_i32_e32 v68, 0x80, v68
	v_min_i32_e32 v69, 0x80, v69
	v_lshl_add_u32 v68, v68, 2, s74
	v_lshl_add_u32 v69, v69, 2, s74
	ds_read_b32 v68, v68 offset:512
	ds_read_b32 v69, v69 offset:512
	v_add_u32_e32 v244, 0x1de, v174
	v_add_u32_e32 v245, 0x1dd, v174
	v_min_i32_e32 v244, 0x80, v244
	v_min_i32_e32 v245, 0x80, v245
	v_lshl_add_u32 v244, v244, 2, s74
	v_lshl_add_u32 v245, v245, 2, s74
	ds_read_b32 v244, v244 offset:512
	ds_read_b32 v245, v245 offset:512
	s_waitcnt lgkmcnt(2)
	v_pk_fma_f32 v[172:173], v[64:65], s[34:35], v[68:69] op_sel_hi:[1,0,1]
	v_max3_f32 v68, v230, v172, v173
	s_waitcnt lgkmcnt(0)
	v_pk_fma_f32 v[174:175], v[66:67], s[34:35], v[244:245] op_sel_hi:[1,0,1]
	s_nop 0
	v_max3_f32 v229, v68, v174, v175
	s_andn2_saveexec_b64 s[0:1], s[0:1]
	s_cbranch_execz .LBB0_159
	s_branch .LBB0_195
